# conservative background-conversion delay (2 x s_sleep 64)
# speedup vs baseline: 1.0027x; 1.0027x over previous
; #define LAS __attribute__((address_space(3)))
; __device__ __forceinline__ void cv_background(Frame& F, const CvPtrs& P, int s) {
;     int tv = threadIdx.x; asm volatile("" : "+v"(tv));
;     const int w = __builtin_amdgcn_readfirstlane(tv >> 6) - 1, lane = tv & 63, nbw = F.G * (NWAVES - 1);
;     LAS float* scr = (LAS float*)(F.lds + RING_OFF + (w + 1) * 16384);
;     const int sh_ = cv_bg_share(s), hi = (sh_ + 1) * CV_BG_PER < CV_BG_TOTAL ? (sh_ + 1) * CV_BG_PER : CV_BG_TOTAL;
;     for (int j = sh_ * CV_BG_PER + F.vcu * (NWAVES - 1) + w; j < hi; j += nbw) {
; __device__ __forceinline__ void xcd_barrier_cv(const XcdBarrier& b, Frame& F, const CvPtrs& P, int s, bool local) {
;     ...
;     else if (cv_bg_share(s) >= 0 && cv_bg_share(s) < CV_BG_SHARES) cv_background(F, P, s);
.LBB0_769:
	s_and_b64 vcc, exec, s[0:1]
	s_cbranch_vccz .LBB0_1015
	s_sleep 64
	s_sleep 64
	v_mov_b32_e32 v4, v0
	s_mov_b64 s[6:7], -1
	v_readfirstlane_b32 s8, v4
	s_mov_b64 s[0:1], 0
	s_cmp_lt_i32 s89, 5
	s_mov_b64 s[4:5], 0
	s_cbranch_scc1 .LBB0_787
	s_cmp_gt_i32 s89, 7
	s_cbranch_scc0 .LBB0_779
	s_cmp_gt_i32 s89, 8
	s_cbranch_scc0 .LBB0_776
	s_cmp_eq_u32 s89, 9
	s_mov_b64 s[4:5], -1
	s_cbranch_scc0 .LBB0_775
	s_mov_b64 s[4:5], 0
